# C1 tiles dealt contiguously per workgroup (tiles 4bx..4bx+3, sample tile 1024+bx on the first 32) instead of stride-256
# baseline (speedup 1.0000x reference)
; #define LAS __attribute__((address_space(3)))
; __global__ void __launch_bounds__(NWAVES * 64, 2) mk_fwd(Args args) {
;     ...
;             {
;                 LAS unsigned* actP = (LAS unsigned*)lds;
;                 const unsigned* w2pl = (const unsigned*)(ws + WS_W2P) + (size_t)l * 2 * 32 * RW;
;                 const float* mu = args.in[13] + (size_t)l * SHIFT_DIM;
;                 const float* w0p = args.in[14] + (size_t)l * RW; const float* w2p = args.in[15] + (size_t)l * 64 * RW;
;                 const float* a0p = args.in[16] + (size_t)l * RW; const float* a2p = args.in[17] + (size_t)l * 64 * RW;
;                 const float* kkp = args.in[18] + (size_t)l * RW; const float* kap = args.in[19] + (size_t)l * RW; const float* rkp = args.in[20] + (size_t)l * RW;
;                 const int h = tid >> 5, kp = tid & 31, c0 = 2 * tid;
;                 const f32x2 mu_r = *(const f32x2*)(mu + c0), mu_k = *(const f32x2*)(mu + RW + c0), mu_v = *(const f32x2*)(mu + 2 * RW + c0);
;                 const f32x2 w0v = *(const f32x2*)(w0p + c0), a0v = *(const f32x2*)(a0p + c0), kkw = *(const f32x2*)(kkp + c0), kaw = *(const f32x2*)(kap + c0), rkw = *(const f32x2*)(rkp + c0);
;                 for (int tile = bx; tile < M / 16; tile += G) {
.LBB0_421:
	v_readlane_b32 s0, v252, 14
	v_readlane_b32 s1, v252, 15
	s_mov_b64 s[4:5], s[0:1]
	s_cmp_le_i32 s4, s10
	v_readlane_b32 s2, v252, 16
	v_readlane_b32 s3, v252, 17
	s_cselect_b64 s[0:1], -1, 0
	s_cmp_lt_i32 s10, s5
	s_cselect_b64 s[2:3], -1, 0
	s_and_b64 s[48:49], s[0:1], s[2:3]
	s_andn2_b64 vcc, exec, s[48:49]
	s_cbranch_vccnz .LBB0_615
	v_writelane_b32 v254, s48, 60
	s_waitcnt vmcnt(0)
	v_mov_b32_e32 v109, v0
	v_readlane_b32 s2, v252, 12
	v_writelane_b32 v254, s49, 61
	s_mov_b64 s[48:49], 0
	v_readlane_b32 s3, v252, 13
	s_add_u32 s52, s2, s48
	s_addc_u32 s53, s3, s49
	v_readlane_b32 s2, v254, 54
	v_readlane_b32 s3, v254, 55
	v_readlane_b32 s95, v252, 0
	s_add_u32 s46, s52, 0x13300000
	s_mov_b32 s3, s11
	v_readlane_b32 s0, v252, 3
	s_mov_b32 s1, s95
	s_addc_u32 s47, s53, 0
	v_writelane_b32 v254, s2, 54
	s_lshl_b64 s[54:55], s[2:3], 10
	v_readfirstlane_b32 s10, v109
	v_writelane_b32 v254, s3, 55
	s_cmpk_gt_i32 s1, 0x41f
	v_and_b32_e32 v127, 31, v109
	s_cbranch_scc1 .LBB0_498
	v_readlane_b32 s8, v254, 54
	s_add_u32 s50, s52, 0x2b800000
	v_readlane_b32 s9, v254, 55
	s_addc_u32 s51, s53, 0
	s_lshl_b64 s[42:43], s[8:9], 18
	s_add_u32 s6, s52, s42
	v_readlane_b32 s56, v252, 52
	s_addc_u32 s7, s53, s43
	v_lshlrev_b32_e32 v36, 1, v109
	s_lshl_b64 s[2:3], s[54:55], 2
	v_readlane_b32 s64, v252, 60
	v_ashrrev_i32_e32 v37, 31, v36
	v_readlane_b32 s65, v252, 61
	s_add_u32 s4, s64, s2
	v_readlane_b32 s62, v252, 58
	s_addc_u32 s5, s65, s3
	v_lshlrev_b64 v[4:5], 2, v[36:37]
	v_readlane_b32 s63, v252, 59
	v_lshl_add_u64 v[6:7], s[4:5], 0, v[4:5]
	s_add_u32 s4, s62, s2
	v_readlane_b32 s60, v252, 56
	s_addc_u32 s5, s63, s3
	v_readlane_b32 s61, v252, 57
	global_load_dwordx2 v[38:39], v[6:7], off
	v_lshl_add_u64 v[6:7], s[4:5], 0, v[4:5]
	s_add_u32 s4, s60, s2
	s_addc_u32 s5, s61, s3
	v_readlane_b32 s57, v252, 53
	v_readlane_b32 s58, v252, 54
	v_readlane_b32 s59, v252, 55
	v_readlane_b32 s66, v252, 62
	v_readlane_b32 s67, v252, 63
	v_readlane_b32 s68, v253, 0
	v_readlane_b32 s69, v253, 1
	v_readlane_b32 s70, v253, 2
	v_readlane_b32 s71, v253, 3
	global_load_dwordx2 v[40:41], v[6:7], off
	v_lshl_add_u64 v[6:7], s[4:5], 0, v[4:5]
	s_add_u32 s4, s56, s2
	s_addc_u32 s5, s57, s3
	v_readlane_b32 s56, v253, 58
	v_readlane_b32 s68, v254, 6
	v_readlane_b32 s69, v254, 7
	s_add_u32 s2, s68, s2
	global_load_dwordx2 v[42:43], v[6:7], off
	v_lshl_add_u64 v[6:7], s[4:5], 0, v[4:5]
	s_addc_u32 s3, s69, s3
	global_load_dwordx2 v[44:45], v[6:7], off
	v_readlane_b32 s66, v254, 4
	v_lshl_add_u64 v[6:7], s[2:3], 0, v[4:5]
	s_mul_i32 s2, s8, 0x3200
	v_readlane_b32 s67, v254, 5
	s_add_u32 s2, s66, s2
	s_addc_u32 s3, s67, 0
	global_load_dwordx2 v[46:47], v[6:7], off
	v_lshl_add_u64 v[6:7], s[2:3], 0, v[4:5]
	s_movk_i32 s4, 0x2000
	v_add_co_u32_e32 v8, vcc, s4, v6
	s_movk_i32 s4, 0x1000
	s_nop 0
	v_addc_co_u32_e32 v9, vcc, 0, v7, vcc
	v_add_co_u32_e32 v10, vcc, s4, v6
	s_lshl_b32 s19, s8, 4
	s_nop 0
	v_addc_co_u32_e32 v11, vcc, 0, v7, vcc
	global_load_dwordx2 v[48:49], v[8:9], off
	global_load_dwordx2 v[50:51], v[10:11], off
	global_load_dwordx2 v[52:53], v[6:7], off
	v_and_b32_e32 v7, 0x7f, v109
	v_or_b32_e32 v6, 0xc00, v7
	s_waitcnt lgkmcnt(0)
	v_lshlrev_b32_e32 v2, 1, v6
	v_lshl_add_u64 v[56:57], s[46:47], 0, v[2:3]
	v_lshlrev_b32_e32 v2, 2, v6
	v_cmp_lt_i32_e32 vcc, v197, v191
	v_lshl_add_u64 v[58:59], s[2:3], 0, v[2:3]
	v_cmp_gt_u32_e64 s[2:3], 64, v7
	v_cndmask_b32_e32 v2, v190, v197, vcc
	v_lshlrev_b32_e32 v88, 2, v2
	v_and_b32_e32 v2, 1, v109
	v_cmp_eq_u32_e64 s[4:5], 0, v2
	v_lshl_add_u32 v2, v7, 5, 0
	v_add_u32_e32 v7, 0x200, v109
	v_ashrrev_i32_e32 v54, 5, v109
	v_lshl_add_u64 v[8:9], s[6:7], 0, v[4:5]
	s_mov_b64 s[6:7], 0x2640000
	v_ashrrev_i32_e32 v90, 7, v7
	v_cmp_gt_u32_e64 s[36:37], s23, v7
	v_add_u32_e32 v7, 0x400, v109
	s_add_u32 s42, s48, s42
	v_lshl_add_u64 v[62:63], v[8:9], 0, s[6:7]
	s_mov_b64 s[6:7], 0x2660000
	v_ashrrev_i32_e32 v55, 31, v54
	v_ashrrev_i32_e32 v92, 7, v7
	v_cmp_gt_u32_e64 s[38:39], s23, v7
	v_add_u32_e32 v7, 0x600, v109
	s_addc_u32 s43, s49, s43
	v_readlane_b32 s56, v254, 29
	v_lshl_add_u64 v[64:65], v[8:9], 0, s[6:7]
	v_lshl_add_u64 v[8:9], v[54:55], 2, s[52:53]
	v_ashrrev_i32_e32 v55, 7, v109
	v_ashrrev_i32_e32 v94, 7, v7
	v_cmp_lt_i32_e32 vcc, v193, v191
	s_add_u32 s42, s56, s42
	v_readlane_b32 s56, v254, 30
	s_mov_b64 s[8:9], 0x2500000
	v_lshl_add_u32 v89, v55, 2, v2
	v_lshl_add_u32 v91, v90, 2, v2
	v_lshl_add_u32 v93, v92, 2, v2
	v_lshl_add_u32 v95, v94, 2, v2
	v_cndmask_b32_e32 v2, v190, v193, vcc
	s_addc_u32 s43, s56, s43
	v_lshl_add_u64 v[60:61], v[36:37], 1, s[46:47]
	v_cmp_eq_u32_e64 s[6:7], 0, v127
	v_lshlrev_b32_e32 v66, 3, v127
	v_mov_b32_e32 v67, v3
	v_lshl_add_u64 v[68:69], v[8:9], 0, s[8:9]
	v_lshlrev_b32_e32 v70, 2, v127
	v_mov_b32_e32 v71, v3
	v_cmp_gt_u32_e64 s[8:9], s23, v109
	v_cmp_gt_u32_e64 s[40:41], s23, v7
	v_lshlrev_b32_e32 v96, 2, v2
	v_lshl_add_u64 v[72:73], s[42:43], 0, v[4:5]
	v_lshlrev_b32_e32 v2, 2, v6
	s_lshl_b32 s96, s1, 2
	v_readlane_b32 s57, v253, 59
	v_readlane_b32 s58, v253, 60
	v_readlane_b32 s59, v253, 61
	v_readlane_b32 s60, v253, 62
	v_readlane_b32 s61, v253, 63
	v_readlane_b32 s62, v254, 0
	v_readlane_b32 s63, v254, 1
	v_readlane_b32 s64, v254, 2
	v_readlane_b32 s65, v254, 3
	v_readlane_b32 s70, v254, 8
	v_readlane_b32 s71, v254, 9
	s_branch .LBB0_425
; __device__ __forceinline__ float bflo(unsigned u) { return __uint_as_float(u << 16); }
; __global__ void __launch_bounds__(NWAVES * 64, 2) mk_fwd(Args args) {
;     ...
;                     for (int tok = 0; tok < 16; ++tok) {
;                         const int m = m0 + tok;
;                         const unsigned ur = pur[tok + 1], uk = puk[tok + 1], uv = puv[tok + 1];
;                         const float cr[2] = {bflo(ur), bfhi(ur)}, ck[2] = {bflo(uk), bfhi(uk)}, cv[2] = {bflo(uv), bfhi(uv)};
;                         float rr[2], kk[2], vv[2], dec[2], aa[2], kkn[2], km[2], bb[2];
;                         rr[0] = cr[0] + (pr[0] - cr[0]) * mu_r.x; rr[1] = cr[1] + (pr[1] - cr[1]) * mu_r.y;
;                         kk[0] = ck[0] + (pk[0] - ck[0]) * mu_k.x; kk[1] = ck[1] + (pk[1] - ck[1]) * mu_k.y;
;                         vv[0] = cv[0] + (pv[0] - cv[0]) * mu_v.x; vv[1] = cv[1] + (pv[1] - cv[1]) * mu_v.y;
;                         dec[0] = __expf(-0.6065306597126334f * sigmoidf_(w0v.x + lw[tok][0])); dec[1] = __expf(-0.6065306597126334f * sigmoidf_(w0v.y + lw[tok][1]));
;                         aa[0] = sigmoidf_(a0v.x + la[tok][0]); aa[1] = sigmoidf_(a0v.y + la[tok][1]);
;                         kkn[0] = kk[0] * kkw.x; kkn[1] = kk[1] * kkw.y;
;                         const float ssq = sum32(kkn[0] * kkn[0] + kkn[1] * kkn[1]);
;                         const float inv = rsqrtf(ssq + 1e-12f);
;                         kkn[0] *= inv; kkn[1] *= inv;
;                         km[0] = kk[0] * (1.f + (aa[0] - 1.f) * kaw.x); km[1] = kk[1] * (1.f + (aa[1] - 1.f) * kaw.y);
;                         bb[0] = kkn[0] * aa[0]; bb[1] = kkn[1] * aa[1];
;                         const float rkd = sum32(rr[0] * km[0] * rkw.x + rr[1] * km[1] * rkw.y);
;                         if (kp == 0) rkdot[(size_t)m * 16 + h] = rkd;
;                         char* rec = scanrec + (rec0 + tok) * REC;
;                         *(f32x2*)(rec + kp * 8) = (f32x2){dec[0], dec[1]};
;                         *(f32x2*)(rec + 256 + kp * 8) = (f32x2){kkn[0], kkn[1]};
;                         *(f32x2*)(rec + 512 + kp * 8) = (f32x2){bb[0], bb[1]};
;                         *(unsigned*)(rec + 768 + kp * 4) = cvtpk(rr[0], rr[1]);
;                         *(unsigned*)(rec + 896 + kp * 4) = cvtpk(km[0], km[1]);
;                         *(unsigned*)(rec + 1024 + kp * 4) = cvtpk(vv[0], vv[1]);
.LBB0_424:
	s_or_b64 exec, exec, s[42:43]
	v_lshlrev_b32_e32 v18, 16, v97
	s_nop 0
	s_nop 0
	v_sub_f32_e32 v7, v12, v18
	v_fmac_f32_e32 v18, v48, v7
	v_add_f32_e32 v12, v46, v101
	v_add_f32_e32 v7, v47, v100
	v_mul_f32_e32 v12, 0xbfb8aa3b, v12
	v_mul_f32_e32 v7, 0xbfb8aa3b, v7
	v_exp_f32_e32 v12, v12
	v_exp_f32_e32 v7, v7
	v_and_b32_e32 v19, 0xffff0000, v97
	v_sub_f32_e32 v6, v6, v19
	v_fmac_f32_e32 v19, v49, v6
	v_add_f32_e32 v6, 1.0, v12
	v_add_f32_e32 v7, 1.0, v7
	s_waitcnt lgkmcnt(1)
	v_add_f32_e32 v12, v17, v20
	v_rcp_f32_e32 v6, v6
	v_rcp_f32_e32 v7, v7
	v_add_f32_e32 v12, 0x2b8cbccc, v12
	v_mul_f32_e32 v17, 0x4b800000, v12
	v_cmp_gt_f32_e32 vcc, s33, v12
	v_mul_f32_e32 v6, 0xbf1b4598, v6
	v_mul_f32_e32 v7, 0xbf1b4598, v7
	v_cndmask_b32_e32 v12, v12, v17, vcc
	v_rsq_f32_e32 v12, v12
	v_mul_f32_e32 v6, 0x3fb8aa3b, v6
	v_mul_f32_e32 v7, 0x3fb8aa3b, v7
	v_exp_f32_e32 v6, v6
	v_exp_f32_e32 v7, v7
	v_mul_f32_e32 v17, 0x45800000, v12
	v_cndmask_b32_e32 v12, v12, v17, vcc
	v_pk_mul_f32 v[4:5], v[4:5], v[12:13] op_sel_hi:[1,0]
	s_add_i32 s96, s96, 1
	s_add_i32 s99, s1, 0x400
	s_cmp_lt_u32 s1, 32
	s_cselect_b32 s99, s99, 0x7fff
	s_and_b32 s98, s96, 3
	s_cselect_b32 s98, s96, s99
	s_cmp_gt_u32 s96, 0x400
	s_cselect_b32 s96, 0x7fff, s98
	v_pk_mul_f32 v[10:11], v[10:11], v[4:5]
	global_store_dwordx2 v[8:9], v[6:7], off offset:896
	global_store_dwordx2 v[8:9], v[4:5], off offset:1152
	global_store_dwordx2 v[8:9], v[10:11], off offset:1408
	v_add_co_u32_e32 v4, vcc, 0x4000, v32
	v_cvt_pk_bf16_f32 v6, v13, v14
	s_cmpk_gt_i32 s96, 0x41f
	s_nop 0
	v_addc_co_u32_e32 v5, vcc, 0, v33, vcc
	global_store_dword v[4:5], v6, off offset:1664
	v_cvt_pk_bf16_f32 v6, v15, v16
	global_store_dword v[4:5], v6, off offset:1792
	v_cvt_pk_bf16_f32 v6, v18, v19
	global_store_dword v[4:5], v6, off offset:1920
	s_cbranch_scc1 .LBB0_498
